# P3 loop: two loop-counter updates fill the MFMA-to-VALU hazard pad after the second QK chain (s_nop 3 -> s_nop 1)
# speedup vs baseline: 1.0084x; 1.0084x over previous
.LBB0_325:
	s_waitcnt lgkmcnt(4)
	v_mfma_f32_32x32x16_bf16 v[96:111], v[80:83], v[144:147], v[64:79]
	v_mfma_f32_32x32x16_bf16 v[96:111], v[202:205], v[140:143], v[96:111]
	s_add_i32 s4, s100, 64
	v_cvt_f32_i32_e32 v156, s4
	v_add_f32_e32 v156, v255, v156
	v_fma_f32 v254, v208, v156, -v207
	s_nop 0
	v_mfma_f32_32x32x16_bf16 v[96:111], v[194:197], v[136:139], v[96:111]
	v_mov_b32_e32 v64, v254
	v_fmamk_f32 v65, v208, 0x3f800000, v254
	v_fmamk_f32 v66, v208, 0x40000000, v254
	v_fmamk_f32 v67, v208, 0x40400000, v254
	v_fmamk_f32 v68, v208, 0x41000000, v254
	v_fmamk_f32 v69, v208, 0x41100000, v254
	v_fmamk_f32 v70, v208, 0x41200000, v254
	v_fmamk_f32 v71, v208, 0x41300000, v254
	v_mfma_f32_32x32x16_bf16 v[96:111], v[186:189], v[132:135], v[96:111]
	v_fmamk_f32 v72, v208, 0x41800000, v254
	v_fmamk_f32 v73, v208, 0x41880000, v254
	v_fmamk_f32 v74, v208, 0x41900000, v254
	v_fmamk_f32 v75, v208, 0x41980000, v254
	v_fmamk_f32 v76, v208, 0x41c00000, v254
	v_fmamk_f32 v77, v208, 0x41c80000, v254
	v_fmamk_f32 v78, v208, 0x41d00000, v254
	v_fmamk_f32 v79, v208, 0x41d80000, v254
	s_add_i32 s3, s79, 0xfffe8000
	s_and_b32 s3, s3, 0x18000
	v_add_u32_e32 v158, s3, v235
	v_add_u32_e32 v159, s3, v239
	v_add_u32_e32 v160, s3, v236
	v_add_u32_e32 v161, s3, v234
	ds_read_b64_tr_b16 v[182:183], v158 offset:32768
	ds_read_b64_tr_b16 v[184:185], v158 offset:34816
	ds_read_b64_tr_b16 v[178:179], v159 offset:32768
	ds_read_b64_tr_b16 v[180:181], v159 offset:34816
	ds_read_b64_tr_b16 v[148:149], v160 offset:32768
	ds_read_b64_tr_b16 v[150:151], v160 offset:34816
	ds_read_b64_tr_b16 v[152:153], v161 offset:32768
	ds_read_b64_tr_b16 v[154:155], v161 offset:34816
	s_waitcnt lgkmcnt(8)
	v_mfma_f32_32x32x16_bf16 v[80:95], v[198:201], v[144:147], v[64:79]
	v_exp_f32_e32 v96, v96
	v_exp_f32_e32 v97, v97
	v_exp_f32_e32 v98, v98
	v_exp_f32_e32 v99, v99
	v_mfma_f32_32x32x16_bf16 v[80:95], v[190:193], v[140:143], v[80:95]
	v_exp_f32_e32 v100, v100
	v_exp_f32_e32 v101, v101
	v_exp_f32_e32 v102, v102
	v_exp_f32_e32 v103, v103
	v_mfma_f32_32x32x16_bf16 v[80:95], v[246:249], v[136:139], v[80:95]
	v_exp_f32_e32 v104, v104
	v_exp_f32_e32 v105, v105
	v_exp_f32_e32 v106, v106
	v_exp_f32_e32 v107, v107
	v_mfma_f32_32x32x16_bf16 v[80:95], v[250:253], v[132:135], v[80:95]
	v_exp_f32_e32 v108, v108
	v_exp_f32_e32 v109, v109
	v_exp_f32_e32 v110, v110
	v_exp_f32_e32 v111, v111
	s_add_i32 s79, s79, 0x8000
	s_add_i32 s100, s100, 64
	s_nop 1
	s_cmp_le_i32 s72, s101
	s_cbranch_scc0 .Lmask_blk
.LBB0_327:
	s_waitcnt lgkmcnt(4)
	v_mfma_f32_32x32x16_bf16 v[48:63], v[182:185], v[174:177], v[48:63]
	v_sub_f32_e32 v190, v80, v237
	v_exp_f32_e32 v190, v190
	ds_read_b64_tr_b16 v[246:247], v158 offset:36864
	ds_read_b64_tr_b16 v[248:249], v158 offset:38912
	v_add_f32_e32 v157, v190, v96
	v_mfma_f32_32x32x16_bf16 v[32:47], v[178:181], v[174:177], v[32:47]
	v_sub_f32_e32 v191, v81, v237
	v_exp_f32_e32 v191, v191
	ds_read_b64_tr_b16 v[250:251], v159 offset:36864
	ds_read_b64_tr_b16 v[252:253], v159 offset:38912
	v_add_f32_e32 v156, v191, v97
	v_add_f32_e32 v157, v156, v157
	s_waitcnt lgkmcnt(4)
	v_mfma_f32_32x32x16_bf16 v[16:31], v[148:151], v[174:177], v[16:31]
	v_sub_f32_e32 v192, v82, v237
	v_exp_f32_e32 v192, v192
	ds_read_b64_tr_b16 v[182:183], v160 offset:36864
	ds_read_b64_tr_b16 v[184:185], v160 offset:38912
	v_add_f32_e32 v156, v192, v98
	v_add_f32_e32 v157, v156, v157
	v_mfma_f32_32x32x16_bf16 v[0:15], v[152:155], v[174:177], v[0:15]
	v_sub_f32_e32 v193, v83, v237
	v_exp_f32_e32 v193, v193
	ds_read_b64_tr_b16 v[178:179], v161 offset:36864
	ds_read_b64_tr_b16 v[180:181], v161 offset:38912
	v_add_f32_e32 v156, v193, v99
	v_add_f32_e32 v157, v156, v157
	v_cvt_pk_bf16_f32 v174, v96, v97
	s_waitcnt lgkmcnt(4)
	v_mfma_f32_32x32x16_bf16 v[48:63], v[246:249], v[162:165], v[48:63]
	v_sub_f32_e32 v194, v84, v237
	v_exp_f32_e32 v194, v194
	ds_read_b64_tr_b16 v[148:149], v158 offset:40960
	ds_read_b64_tr_b16 v[150:151], v158 offset:43008
	v_add_f32_e32 v156, v194, v100
	v_add_f32_e32 v157, v156, v157
	v_cvt_pk_bf16_f32 v175, v98, v99
	v_mfma_f32_32x32x16_bf16 v[32:47], v[250:253], v[162:165], v[32:47]
	v_sub_f32_e32 v195, v85, v237
	v_exp_f32_e32 v195, v195
	ds_read_b64_tr_b16 v[152:153], v159 offset:40960
	ds_read_b64_tr_b16 v[154:155], v159 offset:43008
	v_add_f32_e32 v156, v195, v101
	v_add_f32_e32 v157, v156, v157
	v_cvt_pk_bf16_f32 v176, v100, v101
	s_waitcnt lgkmcnt(4)
	v_mfma_f32_32x32x16_bf16 v[16:31], v[182:185], v[162:165], v[16:31]
	v_sub_f32_e32 v196, v86, v237
	v_exp_f32_e32 v196, v196
	ds_read_b64_tr_b16 v[246:247], v160 offset:40960
	ds_read_b64_tr_b16 v[248:249], v160 offset:43008
	v_add_f32_e32 v156, v196, v102
	v_add_f32_e32 v157, v156, v157
	v_cvt_pk_bf16_f32 v177, v102, v103
	v_mfma_f32_32x32x16_bf16 v[0:15], v[178:181], v[162:165], v[0:15]
	v_sub_f32_e32 v197, v87, v237
	v_exp_f32_e32 v197, v197
	ds_read_b64_tr_b16 v[250:251], v161 offset:40960
	ds_read_b64_tr_b16 v[252:253], v161 offset:43008
	v_add_f32_e32 v156, v197, v103
	v_add_f32_e32 v157, v156, v157
	v_cvt_pk_bf16_f32 v162, v104, v105
	s_waitcnt lgkmcnt(4)
	v_mfma_f32_32x32x16_bf16 v[48:63], v[148:151], v[170:173], v[48:63]
	v_sub_f32_e32 v198, v88, v237
	v_exp_f32_e32 v198, v198
	ds_read_b64_tr_b16 v[182:183], v158 offset:45056
	ds_read_b64_tr_b16 v[184:185], v158 offset:47104
	v_add_f32_e32 v156, v198, v104
	v_add_f32_e32 v157, v156, v157
	v_cvt_pk_bf16_f32 v163, v106, v107
	v_mfma_f32_32x32x16_bf16 v[32:47], v[152:155], v[170:173], v[32:47]
	v_sub_f32_e32 v199, v89, v237
	v_exp_f32_e32 v199, v199
	ds_read_b64_tr_b16 v[178:179], v159 offset:45056
	ds_read_b64_tr_b16 v[180:181], v159 offset:47104
	v_add_f32_e32 v156, v199, v105
	v_add_f32_e32 v157, v156, v157
	v_cvt_pk_bf16_f32 v164, v108, v109
	s_waitcnt lgkmcnt(4)
	v_mfma_f32_32x32x16_bf16 v[16:31], v[246:249], v[170:173], v[16:31]
	v_sub_f32_e32 v200, v90, v237
	v_exp_f32_e32 v200, v200
	ds_read_b64_tr_b16 v[148:149], v160 offset:45056
	ds_read_b64_tr_b16 v[150:151], v160 offset:47104
	v_add_f32_e32 v156, v200, v106
	v_add_f32_e32 v157, v156, v157
	v_cvt_pk_bf16_f32 v165, v110, v111
	v_mfma_f32_32x32x16_bf16 v[0:15], v[250:253], v[170:173], v[0:15]
	v_sub_f32_e32 v201, v91, v237
	v_exp_f32_e32 v201, v201
	ds_read_b64_tr_b16 v[152:153], v161 offset:45056
	ds_read_b64_tr_b16 v[154:155], v161 offset:47104
	v_add_f32_e32 v156, v201, v107
	v_add_f32_e32 v157, v156, v157
	v_cvt_pk_bf16_f32 v170, v190, v191
	s_waitcnt lgkmcnt(4)
	v_mfma_f32_32x32x16_bf16 v[48:63], v[182:185], v[166:169], v[48:63]
	v_sub_f32_e32 v202, v92, v237
	v_exp_f32_e32 v202, v202
	v_cvt_pk_bf16_f32 v171, v192, v193
	v_add_f32_e32 v156, v202, v108
	v_add_f32_e32 v157, v156, v157
	v_mfma_f32_32x32x16_bf16 v[32:47], v[178:181], v[166:169], v[32:47]
	v_sub_f32_e32 v203, v93, v237
	v_exp_f32_e32 v203, v203
	v_cvt_pk_bf16_f32 v172, v194, v195
	v_add_f32_e32 v156, v203, v109
	v_add_f32_e32 v157, v156, v157
	s_waitcnt lgkmcnt(0)
	v_mfma_f32_32x32x16_bf16 v[16:31], v[148:151], v[166:169], v[16:31]
	v_sub_f32_e32 v204, v94, v237
	v_exp_f32_e32 v204, v204
	v_cvt_pk_bf16_f32 v173, v196, v197
	v_add_f32_e32 v156, v204, v110
	v_add_f32_e32 v157, v156, v157
	v_mfma_f32_32x32x16_bf16 v[0:15], v[152:155], v[166:169], v[0:15]
	v_sub_f32_e32 v205, v95, v237
	v_exp_f32_e32 v205, v205
	v_cvt_pk_bf16_f32 v166, v198, v199
	v_add_f32_e32 v156, v205, v111
	v_add_f32_e32 v157, v156, v157
	v_cvt_pk_bf16_f32 v167, v200, v201
	v_cvt_pk_bf16_f32 v168, v202, v203
	v_cvt_pk_bf16_f32 v169, v204, v205
	s_add_i32 s72, s72, 1
	v_add_f32_e32 v229, v229, v157
	v_lshl_add_u64 v[218:219], v[218:219], 0, s[88:89]
	v_lshl_add_u64 v[220:221], v[220:221], 0, s[88:89]
	v_lshl_add_u64 v[224:225], v[224:225], 0, s[92:93]
	s_and_b32 s1, s79, 0x18000
	s_xor_b32 s0, s1, 0x10000
	v_add_u32_e32 v158, s0, v222
	v_add_u32_e32 v159, s0, v223
	v_add_u32_e32 v160, s0, v241
	v_add_u32_e32 v161, s0, v242
	s_cmp_ge_i32 s72, s99
	s_cbranch_scc1 .LBB0_332
	s_cmp_ge_i32 s72, s73
	s_cbranch_scc1 .Lk_last
	s_waitcnt vmcnt(4) lgkmcnt(0)
	s_barrier
	s_branch .Lk_top
